# adds: static s_setprio 1 for waves 4-7 inside the two attention bodies
# baseline (speedup 1.0000x reference)
; #define SBAR() __builtin_amdgcn_sched_barrier(0)
; __device__ __forceinline__ int v_st(int k, int c) { const int kk = (k & ~0xC) | ((k & 4) << 1) | ((k & 8) >> 1); return ((kk >> 3) * 4 + (c >> 5)) * 512 + ((kk & 7) * 32 + (c & 31)) * 2; }
; __device__ __forceinline__ int v_rd_base(int lane) { return ((lane & 3) << 3) | (((lane >> 2) & 3) << 6) | (((lane >> 4) & 1) << 5) | (((lane >> 5) & 1) << 8); }
; #define VMW() asm volatile("s_waitcnt vmcnt(0)" ::: "memory")
; template <class TIn, class TOut, int ost, bool HAS_SS>
; __device__ __forceinline__ void causal_swa_block(const BlockRef<TIn, TOut>& cur_, const BlockRef<TIn, TOut>& nxt_, int skv, int W, char* lds, Seam<TIn>& S, int cbl  ) {
;     ...
;     BlockRef<TIn, TOut> cur, nxt; cur.Q = uptr(cur_.Q); cur.K = uptr(cur_.K); cur.V = uptr(cur_.V); cur.O = uptr(cur_.O); cur.SS = uptr(cur_.SS); cur.P0 = __builtin_amdgcn_readfirstlane(cur_.P0);
;     nxt.Q = uptr(nxt_.Q); nxt.K = uptr(nxt_.K); nxt.V = uptr(nxt_.V); nxt.O = nullptr; nxt.SS = nullptr; nxt.P0 = __builtin_amdgcn_readfirstlane(nxt_.P0);
;     int tid_ = my_tid();
;     const int tid = tid_, wid = __builtin_amdgcn_readfirstlane(tid >> 6), lane = tid & 63, r32 = lane & 31, hi = lane >> 5;
;     const int j_lo = swa_jlo(cur.P0, W);
;     int j_hi = (cur.P0 + QB - 1) / KVBLK + 1; if (j_hi > skv / KVBLK) j_hi = skv / KVBLK;
;     const int NT = j_hi - j_lo;
;     const int kbn = swa_jlo(nxt.P0, W) * KVBLK;
;     const int qlo = cur.P0 + wid * QBLK, qm = qlo + r32 - 4 * hi;
;     char* V_lds = lds; char* K_lds = lds + 2 * SHM_V;
;     float* ws = (float*)(lds + 2 * SHM_V + 2 * SHM_K) + wid * 64; float* li_l = ws, * al_l = ws + 32;
;     float m_reg = -1e30f, l_reg = 0; f32x16 o[4] = {};
;     const int sr = tid >> 4, sc = (tid & 15) * 8, vst0 = v_st(sr, sc), vst1 = v_st(32 + sr, sc), kws = KSWZ(sr, sc * 2);
;     const int vb0 = (int)(uintptr_t)V_lds + v_rd_base(lane);
;     const TIn* Kh = cur.K; const TIn* Vh = cur.V;
;     ...
;     constexpr int NQL = F32 ? 16 : 8;
;     constexpr bool SK = WSKIP && !F32;
;     ...
;     f32x16 pA0, pA1, pB0, pB1; float mnA, mnB, alA, alB; bf16x8 pa0, pa1, pa2, pa3;
;     if constexpr (F32) { VMW(); SWRITE_VF(0); SBAR(); } else { SWRITE_HV(0); SBAR(); }
;     if (NT > 1) { if constexpr (F32) SLOAD_F((const float*)Kh, KBASE(1)); else SLOAD_H(Kh, Vh, KBASE(1)); }
.LBB0_883:
	s_getreg_b32 s12, hwreg(HW_REG_HW_ID, 0, 6)
	s_lshl_b32 s12, s12, 2
	s_and_b32 s12, s12, 0xfc
	s_or_b32 s12, s12, 0x23f00
	v_mov_b32_e32 v0, s12
	ds_read_b32 v0, v0
	s_add_i32 s12, s18, 0xfff00001
	s_lshr_b32 s12, s12, 6
	v_mbcnt_lo_u32_b32 v34, -1, 0
	v_mbcnt_hi_u32_b32 v34, -1, v34
	s_cmp_gt_i32 s18, 0xfffff
	s_waitcnt lgkmcnt(0)
	v_readfirstlane_b32 s13, v0
	s_cselect_b32 s36, s12, 0
	s_cmp_lt_u32 s13, 4
	s_cbranch_scc1 .Lfox_prio_skip
	s_setprio 1
.Lfox_prio_skip:
	s_add_i32 s12, s18, 0xff
	v_lshl_add_u32 v35, s13, 6, v34
	v_ashrrev_i32_e32 v206, 4, v35
	v_and_b32_e32 v3, 0xfffff0, v206
	v_lshlrev_b32_e32 v4, 1, v206
	s_ashr_i32 s13, s12, 31
	v_and_or_b32 v3, v4, 8, v3
	v_lshrrev_b32_e32 v4, 1, v206
	v_and_b32_e32 v5, 3, v206
	v_add_u32_e32 v208, 32, v206
	s_lshr_b32 s13, s13, 26
	v_and_or_b32 v4, v4, 4, v5
	v_and_b32_e32 v5, 0xfffff0, v208
	v_lshlrev_b32_e32 v6, 1, v208
	s_add_i32 s12, s12, s13
	v_lshlrev_b32_e32 v0, 3, v34
	v_and_or_b32 v5, v6, 8, v5
	s_ashr_i32 s12, s12, 6
	v_and_b32_e32 v2, 0x78, v0
	v_lshrrev_b32_e32 v3, 1, v3
	v_bfe_u32 v0, v0, 5, 2
	v_lshrrev_b32_e32 v5, 1, v5
	s_add_i32 s12, s12, 1
	v_or_b32_e32 v3, v3, v0
	v_lshlrev_b32_e32 v207, 1, v2
	v_or_b32_e32 v0, v5, v0
	s_cmpk_lt_i32 s18, 0x701
	v_lshlrev_b32_e32 v3, 9, v3
	v_lshlrev_b32_e32 v4, 6, v4
	v_and_b32_e32 v2, 48, v207
	v_lshlrev_b32_e32 v0, 9, v0
	s_cselect_b32 s17, s12, 32
	v_or3_b32 v3, v3, v4, v2
	v_or3_b32 v0, v0, v4, v2
	v_readfirstlane_b32 s37, v35
	s_sub_i32 s46, s17, s36
	v_add_u32_e32 v215, 0, v3
	v_add_u32_e32 v216, 0, v0
	ds_write_b128 v215, v[112:115]
	ds_write_b128 v216, v[116:119]
	s_cmp_gt_i32 s46, 1
	s_cselect_b64 s[12:13], -1, 0
	s_lshl_b32 s56, s36, 6
	s_cmp_lt_i32 s46, 2
	s_cbranch_scc1 .LBB0_885
	s_add_i32 s16, s56, 64
	v_add_u32_e32 v0, s16, v206
	v_lshl_or_b32 v0, v0, 8, v207
	v_add_u32_e32 v4, s16, v208
	v_lshl_add_u64 v[2:3], s[50:51], 0, v[0:1]
	v_lshl_or_b32 v4, v4, 8, v207
	v_mov_b32_e32 v5, v1
	v_lshl_add_u64 v[6:7], s[50:51], 0, v[4:5]
	flat_load_dwordx4 v[112:115], v[2:3]
	flat_load_dwordx4 v[116:119], v[6:7]
	v_lshl_add_u64 v[2:3], s[14:15], 0, v[0:1]
	v_lshl_add_u64 v[4:5], s[14:15], 0, v[4:5]
	flat_load_dwordx4 v[120:123], v[2:3]
	flat_load_dwordx4 v[124:127], v[4:5]

; __device__ __forceinline__ void xcd_barrier(const XcdBarrier& b) {
;     asm volatile("s_waitcnt vmcnt(0)" ::: "memory");
;     __syncthreads();
;     if (my_tid() == 0) {
;         unsigned* bar = b.bar;
;         __builtin_amdgcn_s_waitcnt(0);
;         unsigned nloc = b.st[0], nx = b.st[1];
;         if (nloc == 0u) { xcd_barrier_complete(bar, b.x, nloc, nx); b.st[0] = nloc; b.st[1] = nx; }
.LBB0_1084:
	s_setprio 0
	s_waitcnt vmcnt(0)
	s_barrier
	s_getreg_b32 s0, hwreg(HW_REG_HW_ID, 0, 6)
	s_lshl_b32 s0, s0, 2
	s_and_b32 s0, s0, 0xfc
	s_or_b32 s0, s0, 0x23f00
	v_mov_b32_e32 v0, s0
	ds_read_b32 v0, v0
	s_waitcnt lgkmcnt(0)
	v_readfirstlane_b32 s0, v0
	v_mbcnt_lo_u32_b32 v0, -1, 0
	v_mbcnt_hi_u32_b32 v0, -1, v0
	s_lshl_b32 s0, s0, 6
	v_sub_u32_e32 v0, 0, v0
	v_cmp_eq_u32_e32 vcc, s0, v0
	s_and_saveexec_b64 s[0:1], vcc
	s_cbranch_execz .LBB0_1136
	s_add_i32 s4, 0, 0x23e00
	v_mov_b32_e32 v0, s4
	s_waitcnt vmcnt(0) expcnt(0) lgkmcnt(0)
	ds_read_b32 v2, v0
	s_add_i32 s4, 0, 0x23e04
	v_mov_b32_e32 v0, s4
	ds_read_b32 v0, v0
	s_waitcnt lgkmcnt(1)
	v_cmp_ne_u32_e32 vcc, 0, v2
	s_cbranch_vccnz .LBB0_1100
	s_mov_b32 s4, 1
	v_mov_b32_e32 v16, 0
	s_branch .LBB0_1088

; template <class TIn, class TOut>
; __device__ __forceinline__ void causal_swa_prime(const BlockRef<TIn, TOut>& cur_, int W, char* lds, Seam<TIn>& S) {
;     BlockRef<TIn, TOut> cur; cur.Q = uptr(cur_.Q); cur.K = uptr(cur_.K); cur.V = uptr(cur_.V); cur.O = nullptr; cur.SS = nullptr; cur.P0 = __builtin_amdgcn_readfirstlane(cur_.P0);
;     constexpr bool F32 = same_t<TIn, float>::v;
;     int tid_ = my_tid();
;     const int tid = tid_, wid = __builtin_amdgcn_readfirstlane(tid >> 6), lane = tid & 63, r32 = lane & 31, hi = lane >> 5;
;     const int sr = tid >> 4, sc = (tid & 15) * 8, kws = KSWZ(sr, sc * 2); char* K_lds = lds + 2 * SHM_V;
;     const int kb0 = swa_jlo(cur.P0, W) * KVBLK;
;     for (int d0 = 0; d0 < 8; ++d0) S.qr[d0] = load8<TIn>((const TIn*)((const char*)cur.Q + (unsigned)((wid * QBLK + r32) * D + d0 * 16 + hi * 8) * (unsigned)sizeof(TIn)));
;     if constexpr (F32) { SLOAD_F((const float*)cur.K, kb0); VMW(); SWRITE_KF(0); SBAR(); SLOAD_F((const float*)cur.V, kb0); }
;     else { SLOAD_H(cur.K, cur.V, kb0); VMW(); SWRITE_HK(0); }
;     __syncthreads();
; }
; template <class TIn, class TOut, int ost, bool HAS_SS>
; __device__ __forceinline__ void causal_swa_block(const BlockRef<TIn, TOut>& cur_, const BlockRef<TIn, TOut>& nxt_, int skv, int W, char* lds, Seam<TIn>& S, int cbl  ) {
;     constexpr bool F32 = same_t<TIn, float>::v;
;     BlockRef<TIn, TOut> cur, nxt; cur.Q = uptr(cur_.Q); cur.K = uptr(cur_.K); cur.V = uptr(cur_.V); cur.O = uptr(cur_.O); cur.SS = uptr(cur_.SS); cur.P0 = __builtin_amdgcn_readfirstlane(cur_.P0);
;     nxt.Q = uptr(nxt_.Q); nxt.K = uptr(nxt_.K); nxt.V = uptr(nxt_.V); nxt.O = nullptr; nxt.SS = nullptr; nxt.P0 = __builtin_amdgcn_readfirstlane(nxt_.P0);
;     int tid_ = my_tid();
;     const int tid = tid_, wid = __builtin_amdgcn_readfirstlane(tid >> 6), lane = tid & 63, r32 = lane & 31, hi = lane >> 5;
;     const int j_lo = swa_jlo(cur.P0, W);
;     int j_hi = (cur.P0 + QB - 1) / KVBLK + 1; if (j_hi > skv / KVBLK) j_hi = skv / KVBLK;
;     const int NT = j_hi - j_lo;
;     const int kbn = swa_jlo(nxt.P0, W) * KVBLK;
;     const int qlo = cur.P0 + wid * QBLK, qm = qlo + r32 - 4 * hi;
;     char* V_lds = lds; char* K_lds = lds + 2 * SHM_V;
;     float* ws = (float*)(lds + 2 * SHM_V + 2 * SHM_K) + wid * 64; float* li_l = ws, * al_l = ws + 32;
;     float m_reg = -1e30f, l_reg = 0; f32x16 o[4] = {};
.LBB0_1521:
	s_ashr_i32 s0, s22, 3
	s_ashr_i32 s1, s0, 31
	s_ashr_i32 s16, s22, 5
	s_and_b32 s23, s18, 0x700
	s_lshl_b64 s[12:13], s[0:1], 19
	s_add_u32 s12, s42, s12
	s_addc_u32 s13, s43, s13
	s_lshl_b32 s14, s23, 8
	s_add_u32 s24, s12, s14
	s_addc_u32 s25, s13, 0
	s_lshl_b64 s[14:15], s[0:1], 16
	s_add_u32 s12, s4, s14
	s_addc_u32 s13, s5, s15
	s_add_u32 s14, s6, s14
	s_addc_u32 s15, s7, s15
	s_ashr_i32 s17, s16, 31
	s_lshl_b64 s[16:17], s[16:17], 21
	s_add_u32 s1, s44, s16
	s_addc_u32 s16, s45, s17
	s_lshl_b32 s17, s23, 10
	s_add_u32 s1, s1, s17
	s_addc_u32 s16, s16, 0
	s_lshl_b32 s0, s0, 8
	s_and_b32 s0, s0, 0x300
	s_add_u32 s0, s1, s0
	s_addc_u32 s1, s16, 0
	s_getreg_b32 s16, hwreg(HW_REG_HW_ID, 0, 6)
	s_lshl_b32 s16, s16, 2
	s_and_b32 s16, s16, 0xfc
	s_or_b32 s16, s16, 0x23f00
	v_mov_b32_e32 v0, s16
	ds_read_b32 v0, v0
	v_mov_b32_e32 v9, v145
	s_waitcnt lgkmcnt(0)
	v_readfirstlane_b32 s16, v0
	s_cmp_lt_u32 s16, 4
	s_cbranch_scc1 .Lxat_prio_skip
	s_setprio 1
.Lxat_prio_skip:
	v_mbcnt_lo_u32_b32 v0, -1, 0
	v_mbcnt_hi_u32_b32 v0, -1, v0
	s_nop 1
	v_lshl_add_u32 v18, s16, 6, v0
	v_lshrrev_b32_e32 v2, 1, v0
	v_readfirstlane_b32 s16, v18
	s_lshr_b32 s16, s16, 1
	s_and_b32 s16, s16, 0xffffe0
	v_and_or_b32 v1, v0, 31, s16
	v_and_b32_e32 v2, 16, v2
	v_lshl_or_b32 v144, v1, 8, v2
	v_lshlrev_b32_e32 v1, 4, v18
	v_lshlrev_b32_e32 v20, 4, v0
	v_and_b32_e32 v19, 0xffffff00, v1
	v_and_b32_e32 v0, 0xf0, v20
	v_lshl_add_u64 v[16:17], s[24:25], 0, v[144:145]
	v_or_b32_e32 v144, v19, v0
	v_add_u32_e32 v8, 0x2000, v144
	v_lshl_add_u64 v[0:1], s[12:13], 0, v[144:145]
	v_lshl_add_u64 v[4:5], s[12:13], 0, v[8:9]
	flat_load_dwordx4 v[0:3], v[0:1]
	s_nop 0
	flat_load_dwordx4 v[4:7], v[4:5]
	s_nop 0
	flat_load_dwordx4 v[124:127], v[16:17]
	flat_load_dwordx4 v[120:123], v[16:17] offset:32
	flat_load_dwordx4 v[116:119], v[16:17] offset:64
	flat_load_dwordx4 v[108:111], v[16:17] offset:96
	flat_load_dwordx4 v[104:107], v[16:17] offset:128
	flat_load_dwordx4 v[96:99], v[16:17] offset:160
	v_lshl_add_u64 v[10:11], s[14:15], 0, v[144:145]
	v_lshl_add_u64 v[12:13], s[14:15], 0, v[8:9]
	flat_load_dwordx4 v[8:11], v[10:11]
	s_nop 0
	flat_load_dwordx4 v[12:15], v[12:13]
	s_nop 0
	flat_load_dwordx4 v[112:115], v[16:17] offset:192
	flat_load_dwordx4 v[100:103], v[16:17] offset:224
	s_movk_i32 s16, 0xf0
	v_and_b32_e32 v16, 0x70, v18
	v_bitop3_b32 v16, v20, v16, s16 bitop3:0x6c
	v_add3_u32 v16, 0, v19, v16
	s_waitcnt vmcnt(0)
	s_waitcnt vmcnt(0) lgkmcnt(0)
	ds_write_b128 v16, v[0:3] offset:32768
	ds_write_b128 v16, v[4:7] offset:40960
	s_waitcnt lgkmcnt(0)
	s_barrier
	s_getreg_b32 s16, hwreg(HW_REG_HW_ID, 0, 6)
	s_lshl_b32 s16, s16, 2
	s_and_b32 s16, s16, 0xfc
	s_or_b32 s16, s16, 0x23f00
	v_mov_b32_e32 v0, s16
	ds_read_b32 v0, v0
	v_mbcnt_lo_u32_b32 v49, -1, 0
	v_mbcnt_hi_u32_b32 v49, -1, v49
	s_waitcnt lgkmcnt(0)
	v_readfirstlane_b32 s16, v0
	s_nop 1
	v_lshl_add_u32 v50, s16, 6, v49
	v_ashrrev_i32_e32 v0, 4, v50
	v_readfirstlane_b32 s16, v50
	v_bfe_u32 v151, v49, 5, 1
	s_ashr_i32 s23, s16, 1
	v_and_b32_e32 v4, 0xfffff0, v0
	v_lshlrev_b32_e32 v5, 1, v0
	v_lshrrev_b32_e32 v6, 1, v0
	v_and_b32_e32 v7, 3, v0
	v_add_u32_e32 v161, 32, v0
	v_and_b32_e32 v150, 31, v49
	v_lshlrev_b32_e32 v157, 2, v151
	v_lshlrev_b32_e32 v48, 8, v0
	s_andn2_b32 s23, s23, 31
	v_and_or_b32 v0, v5, 8, v4
	v_and_or_b32 v4, v6, 4, v7
	v_and_b32_e32 v5, 0xfffff0, v161
	v_lshlrev_b32_e32 v6, 1, v161
	v_lshlrev_b32_e32 v1, 3, v49
	v_sub_u32_e32 v3, v150, v157
	s_add_i32 s17, s23, 0x10000
	v_and_or_b32 v5, v6, 8, v5
	v_and_b32_e32 v2, 0x78, v1
	v_bfe_u32 v1, v1, 5, 2
	v_lshrrev_b32_e32 v0, 1, v0
	v_add_u32_e32 v156, s17, v3
	v_lshrrev_b32_e32 v3, 1, v5
	v_lshlrev_b32_e32 v160, 1, v2
	v_or_b32_e32 v0, v0, v1
	v_or_b32_e32 v1, v3, v1
	v_and_b32_e32 v2, 48, v160
	v_lshlrev_b32_e32 v4, 6, v4
	v_lshlrev_b32_e32 v0, 9, v0
	v_lshlrev_b32_e32 v1, 9, v1
	v_or3_b32 v0, v0, v4, v2
	v_or3_b32 v1, v1, v4, v2
	v_add_u32_e32 v168, 0, v0
	v_add_u32_e32 v169, 0, v1
	ds_write_b128 v168, v[8:11]
	ds_write_b128 v169, v[12:15]
	v_or_b32_e32 v146, v48, v160
	v_add_u32_e32 v144, 0x4000, v146
	v_lshl_add_u64 v[0:1], s[14:15], 0, v[144:145]
	v_add_u32_e32 v2, 0x6000, v146
	v_mov_b32_e32 v3, v145
	v_lshl_add_u64 v[4:5], s[14:15], 0, v[2:3]
	flat_load_dwordx4 v[32:35], v[0:1]
	flat_load_dwordx4 v[36:39], v[4:5]
	v_lshl_add_u64 v[0:1], s[12:13], 0, v[144:145]
	v_lshl_add_u64 v[2:3], s[12:13], 0, v[2:3]
	flat_load_dwordx4 v[40:43], v[0:1]
	flat_load_dwordx4 v[44:47], v[2:3]
	v_lshlrev_b32_e32 v0, 4, v49
	v_lshlrev_b32_e32 v51, 4, v151
	v_and_b32_e32 v77, 0x70, v0
	v_lshlrev_b32_e32 v76, 8, v150
	v_xad_u32 v0, v51, v77, 0
	v_add_u32_e32 v147, v0, v76
	ds_read_b128 v[0:3], v147 offset:32768
	ds_read_b128 v[52:55], v147 offset:32896
	v_or_b32_e32 v4, 32, v51
	s_waitcnt lgkmcnt(0)
	v_mfma_f32_32x32x16_bf16 v[16:31], v[0:3], v[124:127], 0
	ds_read_b128 v[0:3], v147 offset:40960
	ds_read_b128 v[56:59], v147 offset:41088
	v_xad_u32 v4, v4, v77, 0
	v_add_u32_e32 v163, v4, v76
	ds_read_b128 v[60:63], v163 offset:32768
	ds_read_b128 v[64:67], v163 offset:32896
	v_or_b32_e32 v68, 64, v51
	v_xad_u32 v68, v68, v77, 0
	s_waitcnt lgkmcnt(0)
	v_mfma_f32_32x32x16_bf16 v[16:31], v[60:63], v[120:123], v[16:31]
	ds_read_b128 v[60:63], v163 offset:40960
	v_add_u32_e32 v164, v68, v76
	ds_read_b128 v[68:71], v163 offset:41088
	v_or_b32_e32 v51, 0x60, v51
	v_xad_u32 v51, v51, v77, 0
	v_add_u32_e32 v165, v51, v76
	s_add_i32 s17, s23, 0xffc1
	v_mfma_f32_32x32x16_bf16 v[0:15], v[0:3], v[124:127], 0
	s_cmp_lt_u32 s17, 0xfffa2
	s_waitcnt lgkmcnt(0)
	v_mfma_f32_32x32x16_bf16 v[0:15], v[60:63], v[120:123], v[0:15]
	ds_read_b128 v[60:63], v164 offset:32768
	ds_read_b128 v[72:75], v164 offset:32896
	ds_read_b128 v[76:79], v164 offset:41088
	s_waitcnt lgkmcnt(0)
	v_mfma_f32_32x32x16_bf16 v[16:31], v[60:63], v[116:119], v[16:31]
	ds_read_b128 v[60:63], v164 offset:40960
	s_waitcnt lgkmcnt(0)
	v_mfma_f32_32x32x16_bf16 v[0:15], v[60:63], v[116:119], v[0:15]
	ds_read_b128 v[60:63], v165 offset:32768
	ds_read_b128 v[80:83], v165 offset:32896
	s_waitcnt lgkmcnt(0)
	v_mfma_f32_32x32x16_bf16 v[16:31], v[60:63], v[108:111], v[16:31]
	ds_read_b128 v[60:63], v165 offset:40960
	ds_read_b128 v[84:87], v165 offset:41088
	s_waitcnt lgkmcnt(0)
	v_mfma_f32_32x32x16_bf16 v[0:15], v[60:63], v[108:111], v[0:15]
	v_mfma_f32_32x32x16_bf16 v[16:31], v[52:55], v[104:107], v[16:31]
	v_mfma_f32_32x32x16_bf16 v[0:15], v[56:59], v[104:107], v[0:15]
	v_mfma_f32_32x32x16_bf16 v[16:31], v[64:67], v[96:99], v[16:31]
	v_mfma_f32_32x32x16_bf16 v[0:15], v[68:71], v[96:99], v[0:15]
	v_mfma_f32_32x32x16_bf16 v[16:31], v[72:75], v[112:115], v[16:31]
	v_mfma_f32_32x32x16_bf16 v[0:15], v[76:79], v[112:115], v[0:15]
	v_mfma_f32_32x32x16_bf16 v[16:31], v[80:83], v[100:103], v[16:31]
	v_mfma_f32_32x32x16_bf16 v[0:15], v[84:87], v[100:103], v[0:15]
	s_cbranch_scc1 .LBB0_1523
; __device__ __forceinline__ void mask_tile(f32x16& p0, f32x16& p1, int dq, unsigned W) {
;     const float NEG = -__builtin_inff();
; #pragma unroll
;     for (int r = 0; r < 16; ++r) {
;         const int c = (r & 3) + 8 * (r >> 2);
;         if ((unsigned)(dq - c) >= W) p0[r] = NEG;
;         if ((unsigned)(dq - c - 32) >= W) p1[r] = NEG;
;     }
; }
	s_mov_b32 s17, 0x100000
	v_cmp_gt_u32_e32 vcc, s17, v156
	v_add_u32_e32 v51, 0xffefffe0, v156
	s_nop 6
	v_cndmask_b32_e32 v16, v148, v16, vcc
	v_cmp_lt_u32_e32 vcc, s20, v51
	v_add_u32_e32 v51, 0xffefffff, v156
	s_nop 0
	v_cndmask_b32_e32 v0, v148, v0, vcc
	v_cmp_lt_u32_e32 vcc, s20, v51
	v_add_u32_e32 v51, 0xffefffdf, v156
	s_nop 0
	v_cndmask_b32_e32 v17, v148, v17, vcc
	v_cmp_lt_u32_e32 vcc, s20, v51
	v_add_u32_e32 v51, 0xffeffffe, v156
	s_nop 0
	v_cndmask_b32_e32 v1, v148, v1, vcc
	v_cmp_lt_u32_e32 vcc, s20, v51
	v_add_u32_e32 v51, 0xffefffde, v156
	s_nop 0
	v_cndmask_b32_e32 v18, v148, v18, vcc
	v_cmp_lt_u32_e32 vcc, s20, v51
	v_add_u32_e32 v51, 0xffeffffd, v156
	s_nop 0
	v_cndmask_b32_e32 v2, v148, v2, vcc
	v_cmp_lt_u32_e32 vcc, s20, v51
	v_add_u32_e32 v51, 0xffefffdd, v156
	s_nop 0
	v_cndmask_b32_e32 v19, v148, v19, vcc
	v_cmp_lt_u32_e32 vcc, s20, v51
	v_add_u32_e32 v51, 0xffeffff8, v156
	s_nop 0
	v_cndmask_b32_e32 v3, v148, v3, vcc
	v_cmp_lt_u32_e32 vcc, s20, v51
	v_add_u32_e32 v51, 0xffefffd8, v156
	s_nop 0
	v_cndmask_b32_e32 v20, v148, v20, vcc
	v_cmp_lt_u32_e32 vcc, s20, v51
	v_add_u32_e32 v51, 0xffeffff7, v156
	s_nop 0
	v_cndmask_b32_e32 v4, v148, v4, vcc
	v_cmp_lt_u32_e32 vcc, s20, v51
	v_add_u32_e32 v51, 0xffefffd7, v156
	s_nop 0
	v_cndmask_b32_e32 v21, v148, v21, vcc
	v_cmp_lt_u32_e32 vcc, s20, v51
	v_add_u32_e32 v51, 0xffeffff6, v156
	s_nop 0
	v_cndmask_b32_e32 v5, v148, v5, vcc
	v_cmp_lt_u32_e32 vcc, s20, v51
	v_add_u32_e32 v51, 0xffefffd6, v156
	s_nop 0
	v_cndmask_b32_e32 v22, v148, v22, vcc
	v_cmp_lt_u32_e32 vcc, s20, v51
	v_add_u32_e32 v51, 0xffeffff5, v156
	s_nop 0
	v_cndmask_b32_e32 v6, v148, v6, vcc
	v_cmp_lt_u32_e32 vcc, s20, v51
	v_add_u32_e32 v51, 0xffefffd5, v156
	s_nop 0
	v_cndmask_b32_e32 v23, v148, v23, vcc
	v_cmp_lt_u32_e32 vcc, s20, v51
	v_add_u32_e32 v51, 0xffeffff0, v156
	s_nop 0
	v_cndmask_b32_e32 v7, v148, v7, vcc
	v_cmp_lt_u32_e32 vcc, s20, v51
	v_add_u32_e32 v51, 0xffefffd0, v156
	s_nop 0
	v_cndmask_b32_e32 v24, v148, v24, vcc
	v_cmp_lt_u32_e32 vcc, s20, v51
	v_add_u32_e32 v51, 0xffefffef, v156
	s_nop 0
	v_cndmask_b32_e32 v8, v148, v8, vcc
	v_cmp_lt_u32_e32 vcc, s20, v51
	v_add_u32_e32 v51, 0xffefffcf, v156
	s_nop 0
	v_cndmask_b32_e32 v25, v148, v25, vcc
	v_cmp_lt_u32_e32 vcc, s20, v51
	v_add_u32_e32 v51, 0xffefffee, v156
	s_nop 0
	v_cndmask_b32_e32 v9, v148, v9, vcc
	v_cmp_lt_u32_e32 vcc, s20, v51
	v_add_u32_e32 v51, 0xffefffce, v156
	s_nop 0
	v_cndmask_b32_e32 v26, v148, v26, vcc
	v_cmp_lt_u32_e32 vcc, s20, v51
	v_add_u32_e32 v51, 0xffefffed, v156
	s_nop 0
	v_cndmask_b32_e32 v10, v148, v10, vcc
	v_cmp_lt_u32_e32 vcc, s20, v51
	v_add_u32_e32 v51, 0xffefffcd, v156
	s_nop 0
	v_cndmask_b32_e32 v27, v148, v27, vcc
	v_cmp_lt_u32_e32 vcc, s20, v51
	v_add_u32_e32 v51, 0xffefffe8, v156
	s_nop 0
	v_cndmask_b32_e32 v11, v148, v11, vcc
	v_cmp_lt_u32_e32 vcc, s20, v51
	v_add_u32_e32 v51, 0xffefffc8, v156
	s_nop 0
	v_cndmask_b32_e32 v28, v148, v28, vcc
	v_cmp_lt_u32_e32 vcc, s20, v51
	v_add_u32_e32 v51, 0xffefffe7, v156
	s_nop 0
	v_cndmask_b32_e32 v12, v148, v12, vcc
	v_cmp_lt_u32_e32 vcc, s20, v51
	v_add_u32_e32 v51, 0xffefffc7, v156
	s_nop 0
	v_cndmask_b32_e32 v29, v148, v29, vcc
	v_cmp_lt_u32_e32 vcc, s20, v51
	v_add_u32_e32 v51, 0xffefffe6, v156
	s_nop 0
	v_cndmask_b32_e32 v13, v148, v13, vcc
	v_cmp_lt_u32_e32 vcc, s20, v51
	v_add_u32_e32 v51, 0xffefffc6, v156
	s_nop 0
	v_cndmask_b32_e32 v30, v148, v30, vcc
	v_cmp_lt_u32_e32 vcc, s20, v51
	v_add_u32_e32 v51, 0xffefffe5, v156
	s_nop 0
	v_cndmask_b32_e32 v14, v148, v14, vcc
	v_cmp_lt_u32_e32 vcc, s20, v51
	v_add_u32_e32 v51, 0xffefffc5, v156
	s_nop 0
	v_cndmask_b32_e32 v31, v148, v31, vcc
	v_cmp_lt_u32_e32 vcc, s20, v51
	s_nop 1
	v_cndmask_b32_e32 v15, v148, v15, vcc
